# convert phase x->bf16 row loop: four row loads issued together, next row prefetched into a second register buffer, loop-top wait vmcnt(3)
# speedup vs baseline: 1.0101x; 1.0101x over previous
.LBB0_107:
	s_waitcnt vmcnt(0)
	v_ashrrev_i32_e32 v0, 6, v38
	v_lshl_add_u32 v0, s28, 2, v0
	s_movk_i32 s0, 0x4000
	v_cmp_gt_i32_e32 vcc, s0, v0
	v_mbcnt_lo_u32_b32 v8, -1, 0
	s_and_saveexec_b64 s[4:5], vcc
	s_cbranch_execz .LBB0_112
	v_mbcnt_hi_u32_b32 v1, -1, v8
	v_and_b32_e32 v2, 64, v1
	v_add_u32_e32 v2, 64, v2
	v_xor_b32_e32 v3, 32, v1
	v_cmp_lt_i32_e64 s[2:3], v3, v2
	v_and_b32_e32 v15, 63, v38
	v_lshlrev_b32_e32 v4, 2, v15
	v_cndmask_b32_e64 v3, v1, v3, s[2:3]
	v_lshlrev_b32_e32 v9, 2, v3
	v_xor_b32_e32 v3, 16, v1
	v_cmp_lt_i32_e64 s[2:3], v3, v2
	v_mov_b32_e32 v5, 0
	v_readlane_b32 s8, v250, 9
	v_cndmask_b32_e64 v3, v1, v3, s[2:3]
	v_lshlrev_b32_e32 v10, 2, v3
	v_xor_b32_e32 v3, 8, v1
	v_cmp_lt_i32_e64 s[2:3], v3, v2
	v_readlane_b32 s10, v250, 11
	v_readlane_b32 s11, v250, 12
	v_cndmask_b32_e64 v3, v1, v3, s[2:3]
	v_lshlrev_b32_e32 v11, 2, v3
	v_xor_b32_e32 v3, 4, v1
	v_cmp_lt_i32_e64 s[2:3], v3, v2
	v_readlane_b32 s0, v250, 13
	v_readlane_b32 s12, v250, 19
	v_cndmask_b32_e64 v3, v1, v3, s[2:3]
	v_lshlrev_b32_e32 v12, 2, v3
	v_xor_b32_e32 v3, 2, v1
	v_cmp_lt_i32_e64 s[2:3], v3, v2
	s_lshl_b32 s6, s0, 3
	v_readlane_b32 s13, v250, 20
	v_cndmask_b32_e64 v3, v1, v3, s[2:3]
	v_lshlrev_b32_e32 v13, 2, v3
	v_xor_b32_e32 v3, 1, v1
	v_cmp_lt_i32_e64 s[2:3], v3, v2
	v_readlane_b32 s1, v250, 14
	v_readlane_b32 s9, v250, 10
	v_cndmask_b32_e64 v1, v1, v3, s[2:3]
	v_lshlrev_b32_e32 v14, 2, v1
	v_ashrrev_i32_e32 v1, 31, v0
	v_lshlrev_b64 v[2:3], 6, v[0:1]
	v_lshl_add_u64 v[2:3], v[2:3], 0, v[4:5]
	v_lshlrev_b64 v[4:5], 11, v[0:1]
	v_lshl_add_u64 v[2:3], s[10:11], 0, v[2:3]
	s_mov_b64 s[2:3], 0xf900000
	v_lshl_or_b32 v4, v15, 4, v4
	v_lshlrev_b64 v[6:7], 12, v[0:1]
	v_lshl_add_u64 v[2:3], v[2:3], 0, s[2:3]
	v_lshl_add_u64 v[4:5], s[10:11], 0, v[4:5]
	s_mov_b64 s[2:3], 0x5800000
	v_lshl_or_b32 v6, v15, 5, v6
	s_ashr_i32 s7, s6, 31
	v_lshl_add_u64 v[4:5], v[4:5], 0, s[2:3]
	v_readlane_b32 s14, v250, 21
	v_readlane_b32 s15, v250, 22
	v_lshl_add_u64 v[6:7], s[12:13], 0, v[6:7]
	s_mov_b64 s[2:3], 0x800
	v_cmp_gt_u32_e32 vcc, 16, v15
	v_cmp_eq_u32_e64 s[0:1], 0, v15
	s_lshl_b64 s[8:9], s[6:7], 6
	s_lshl_b64 s[10:11], s[6:7], 11
	v_lshl_add_u64 v[6:7], v[6:7], 0, s[2:3]
	s_lshl_b64 s[12:13], s[6:7], 12
	s_mov_b64 s[14:15], 0
	s_movk_i32 s7, 0x3fff
	v_readlane_b32 s16, v250, 23
	v_readlane_b32 s17, v250, 24
	v_readlane_b32 s18, v250, 25
	v_readlane_b32 s19, v250, 26
	v_readlane_b32 s20, v250, 27
	v_readlane_b32 s21, v250, 28
	v_readlane_b32 s22, v250, 29
	v_readlane_b32 s23, v250, 30
	v_readlane_b32 s24, v250, 31
	v_readlane_b32 s25, v250, 32
	v_readlane_b32 s26, v250, 33
	v_readlane_b32 s27, v250, 34
	global_load_dwordx4 v[32:35], v[6:7], off offset:-2048
	global_load_dwordx4 v[36:39], v[6:7], off offset:-2032
	global_load_dwordx4 v[40:43], v[6:7], off
	global_load_dwordx4 v[44:47], v[6:7], off offset:16
	s_waitcnt vmcnt(0)
	s_branch .Lcvx_body

.LBB0_110:
	s_waitcnt vmcnt(3) lgkmcnt(0)
.Lcvx_body:
	v_mov_b64_e32 v[16:17], v[32:33]
	v_mov_b64_e32 v[18:19], v[34:35]
	v_mov_b64_e32 v[20:21], v[36:37]
	v_mov_b64_e32 v[22:23], v[38:39]
	v_mov_b64_e32 v[24:25], v[40:41]
	v_mov_b64_e32 v[26:27], v[42:43]
	v_mov_b64_e32 v[28:29], v[44:45]
	v_mov_b64_e32 v[30:31], v[46:47]
	v_add_u32_e32 v48, s6, v0
	v_cmp_ge_i32_e64 s[28:29], s7, v48
	s_and_saveexec_b64 s[30:31], s[28:29]
	s_cbranch_execz .Lcvx_nopf
	v_lshl_add_u64 v[48:49], v[6:7], 0, s[12:13]
	global_load_dwordx4 v[32:35], v[48:49], off offset:-2048
	global_load_dwordx4 v[36:39], v[48:49], off offset:-2032
	global_load_dwordx4 v[40:43], v[48:49], off
	global_load_dwordx4 v[44:47], v[48:49], off offset:16
.Lcvx_nopf:
	s_or_b64 exec, exec, s[30:31]
	v_cvt_pk_bf16_f32 v50, v16, v17
	v_cvt_pk_bf16_f32 v51, v18, v19
	v_cvt_pk_bf16_f32 v52, v20, v21
	v_cvt_pk_bf16_f32 v53, v22, v23
	global_store_dwordx4 v[4:5], v[50:53], off
	v_mul_f32_e32 v1, v17, v17
	v_fmac_f32_e32 v1, v16, v16
	v_fmac_f32_e32 v1, v18, v18
	v_fmac_f32_e32 v1, v19, v19
	v_fmac_f32_e32 v1, v20, v20
	v_fmac_f32_e32 v1, v21, v21
	v_fmac_f32_e32 v1, v22, v22
	v_fmac_f32_e32 v1, v23, v23
	v_mul_f32_e32 v15, v25, v25
	v_fmac_f32_e32 v15, v24, v24
	v_fmac_f32_e32 v15, v26, v26
	v_fmac_f32_e32 v15, v27, v27
	v_fmac_f32_e32 v15, v28, v28
	v_fmac_f32_e32 v15, v29, v29
	v_fmac_f32_e32 v15, v30, v30
	v_fmac_f32_e32 v15, v31, v31
	v_add_f32_e32 v1, v1, v15
	ds_bpermute_b32 v15, v9, v1
	v_cvt_pk_bf16_f32 v16, v24, v25
	v_cvt_pk_bf16_f32 v17, v26, v27
	v_cvt_pk_bf16_f32 v18, v28, v29
	v_cvt_pk_bf16_f32 v19, v30, v31
	s_waitcnt lgkmcnt(0)
	v_add_f32_e32 v1, v1, v15
	ds_bpermute_b32 v15, v10, v1
	global_store_dwordx4 v[4:5], v[16:19], off offset:1024
	s_waitcnt lgkmcnt(0)
	v_add_f32_e32 v1, v1, v15
	ds_bpermute_b32 v15, v11, v1
	s_waitcnt lgkmcnt(0)
	v_add_f32_e32 v1, v1, v15
	ds_bpermute_b32 v15, v12, v1
	s_waitcnt lgkmcnt(0)
	v_add_f32_e32 v1, v1, v15
	ds_bpermute_b32 v15, v13, v1
	s_waitcnt lgkmcnt(0)
	v_add_f32_e32 v1, v1, v15
	ds_bpermute_b32 v15, v14, v1
	s_and_saveexec_b64 s[2:3], vcc
	s_cbranch_execz .LBB0_109
	s_waitcnt lgkmcnt(0)
	v_add_f32_e32 v1, v1, v15
	v_cndmask_b32_e64 v1, 0, v1, s[0:1]
	global_store_dword v[2:3], v1, off
	s_branch .LBB0_109
